# q and kv projection items: first two GEMM K-tiles' LDS-DMA loads issued before the row-scale pass
# speedup vs baseline: 1.0307x; 1.0012x over previous
; DEV float bflo(unsigned w) { return __uint_as_float(w << 16); }
; DEV float bfhi(unsigned w) { return __uint_as_float(w & 0xffff0000u); }
; template <int WN, int WT>
; DEV void gemm_mainloop(const u16* __restrict__ Wt, long ldw, const u16* __restrict__ A, long lda, int K,
;                        char* smem, int tid, f32x4 (&acc)[WN][WT]) {
;     ...
;   __syncthreads();
;   stage_tile<NR>(Wt, ldw, 0, smem, tid);
;   stage_tile<TR>(A, lda, 0, smem + WB, tid);
;   if (nk > 1) {
;     stage_tile<NR>(Wt, ldw, 64, smem + STG, tid);
;     stage_tile<TR>(A, lda, 64, smem + STG + WB, tid);
;   }
; DEV void row_scales(const u16* __restrict__ zrow0, int col0, int ncol, float* rs, int tid) {
;   if (tid >= 384) return;
;   const int r = tid >> 1, h = tid & 1, lane = tid & 63;
;   const u16* s = zrow0 + (long)r * NINP + col0 + h * (ncol / 2);
;   float ss = 0.f;
;   for (int i = 0; i < ncol / 2; i += 8) {
;     uint4 v = *(const uint4*)(s + i);
;     ss += bflo(v.x) * bflo(v.x) + bfhi(v.x) * bfhi(v.x) + bflo(v.y) * bflo(v.y) + bfhi(v.y) * bfhi(v.y) +
;           bflo(v.z) * bflo(v.z) + bfhi(v.z) * bfhi(v.z) + bflo(v.w) * bflo(v.w) + bfhi(v.w) * bfhi(v.w);
;   }
;   ss += shx(ss, 1, lane);
;   if (h == 0) rs[r] = rsqrtf(ss / (float)ncol + 1e-6f);
; }
.LBB0_755:
	s_and_b64 vcc, exec, s[6:7]
	s_cbranch_vccz .LBB0_765
	s_add_i32 s6, s15, 0xffb8
	s_and_b32 s7, s6, 0xff
	s_and_b32 s11, s7, 7
	s_lshr_b32 s6, s7, 3
	v_readlane_b32 s7, v255, 10
	s_add_i32 s10, s7, s6
	s_mul_i32 s6, s10, 0x330000
	s_add_u32 s6, s88, s6
	s_movk_i32 s8, 0x180
	s_addc_u32 s7, s89, 0
	v_cmp_gt_i32_e32 vcc, s8, v58
	s_barrier
	s_mov_b32 s100, s6
	s_mov_b32 s101, s7
	v_ashrrev_i32_e32 v2, 3, v58
	s_and_b32 s11, 0xffff, s11
	s_waitcnt lgkmcnt(0)
	v_lshrrev_b32_e32 v12, 4, v58
	v_ashrrev_i32_e32 v3, 31, v2
	s_lshl_b32 s8, s11, 15
	v_xor_b32_e32 v0, v12, v58
	v_lshlrev_b64 v[4:5], 8, v[2:3]
	v_add_u32_e32 v3, 0x200, v58
	s_add_u32 s8, s12, s8
	v_lshlrev_b32_e32 v0, 4, v0
	v_ashrrev_i32_e32 v6, 3, v3
	s_addc_u32 s9, s13, 0
	v_and_b32_e32 v156, 0x70, v0
	v_ashrrev_i32_e32 v7, 31, v6
	s_waitcnt lgkmcnt(0)
	v_lshl_add_u64 v[0:1], s[8:9], 0, v[156:157]
	v_lshlrev_b32_e32 v13, 4, v58
	v_lshlrev_b64 v[8:9], 8, v[6:7]
	v_lshl_add_u64 v[4:5], v[0:1], 0, v[4:5]
	v_readfirstlane_b32 s8, v13
	v_lshl_add_u64 v[0:1], v[0:1], 0, v[8:9]
	v_lshlrev_b32_e32 v14, 4, v3
	v_lshl_add_u64 v[8:9], s[6:7], 0, v[156:157]
	s_mov_b32 m0, s8
	v_readfirstlane_b32 s8, v14
	v_mad_i64_i32 v[2:3], s[6:7], v2, s33, v[8:9]
	v_add_u32_e32 v7, 0x4000, v13
	s_barrier
	global_load_lds_dwordx4 v[4:5], off
	s_mov_b32 m0, s8
	v_readfirstlane_b32 s6, v7
	global_load_lds_dwordx4 v[0:1], off
	s_mov_b64 s[8:9], 0x200
	s_mov_b32 m0, s6
	v_mad_i64_i32 v[6:7], s[6:7], v6, s33, v[8:9]
	v_add_u32_e32 v15, 0x4000, v14
	v_lshl_add_u64 v[10:11], v[2:3], 0, s[8:9]
	v_readfirstlane_b32 s6, v15
	global_load_lds_dwordx4 v[10:11], off
	v_lshl_add_u64 v[10:11], v[6:7], 0, s[8:9]
	s_mov_b32 m0, s6
	v_add_u32_e32 v15, 0x400, v58
	global_load_lds_dwordx4 v[10:11], off
	v_ashrrev_i32_e32 v10, 3, v15
	v_lshlrev_b32_e32 v15, 4, v15
	v_mad_i64_i32 v[8:9], s[6:7], v10, s33, v[8:9]
	v_add_u32_e32 v16, 0x4000, v15
	v_lshl_add_u64 v[10:11], v[8:9], 0, s[8:9]
	v_readfirstlane_b32 s6, v16
	s_mov_b32 m0, s6
	v_lshl_add_u64 v[4:5], v[4:5], 0, s[34:35]
	global_load_lds_dwordx4 v[10:11], off
	v_add_u32_e32 v10, 0xa000, v13
	v_lshl_add_u64 v[0:1], v[0:1], 0, s[34:35]
	v_readfirstlane_b32 s6, v10
	s_mov_b32 m0, s6
	s_mov_b64 s[8:9], 0x280
	global_load_lds_dwordx4 v[4:5], off
	v_add_u32_e32 v4, 0xa000, v14
	s_mov_b32 s16, 0
	v_readfirstlane_b32 s6, v4
	s_mov_b32 m0, s6
	v_bfe_u32 v4, v58, 1, 3
	global_load_lds_dwordx4 v[0:1], off
	v_lshl_add_u64 v[0:1], v[2:3], 0, s[8:9]
	v_add_u32_e32 v2, 0xe000, v13
	v_lshrrev_b32_e32 v3, 1, v58
	v_readfirstlane_b32 s6, v2
	v_add_u32_e32 v2, 0xe000, v14
	s_mov_b32 m0, s6
	v_readfirstlane_b32 s6, v2
	v_add_u32_e32 v2, 0xe000, v15
	global_load_lds_dwordx4 v[0:1], off
	v_lshl_add_u64 v[0:1], v[6:7], 0, s[8:9]
	s_mov_b32 m0, s6
	v_readfirstlane_b32 s6, v2
	global_load_lds_dwordx4 v[0:1], off
	v_lshl_add_u64 v[0:1], v[8:9], 0, s[8:9]
	s_mov_b32 m0, s6
	v_and_b32_e32 v2, 15, v58
	global_load_lds_dwordx4 v[0:1], off
	s_mov_b32 s6, s100
	s_mov_b32 s7, s101
	s_mov_b32 s98, s16
	v_mov_b32_e32 v133, v2
	v_mov_b32_e32 v134, v3
	v_mov_b32_e32 v135, v4
	v_mov_b32_e32 v136, v12
	s_and_saveexec_b64 s[8:9], vcc
	s_cbranch_execz .LBB0_759
	v_ashrrev_i32_e32 v16, 1, v58
	v_and_b32_e32 v17, 1, v58
	v_mov_b64_e32 v[0:1], s[6:7]
	v_mad_i64_i32 v[0:1], s[16:17], v16, s33, v[0:1]
	v_lshlrev_b32_e32 v156, 7, v17
	s_waitcnt lgkmcnt(0)
	v_lshl_add_u64 v[12:13], v[0:1], 0, v[156:157]
	global_load_dwordx4 v[0:3], v[12:13], off offset:560
	global_load_dwordx4 v[4:7], v[12:13], off offset:544
	global_load_dwordx4 v[8:11], v[12:13], off offset:528
	global_load_dwordx4 v[18:21], v[12:13], off offset:512
	global_load_dwordx4 v[100:103], v[12:13], off offset:624
	global_load_dwordx4 v[104:107], v[12:13], off offset:608
	global_load_dwordx4 v[108:111], v[12:13], off offset:592
	global_load_dwordx4 v[112:115], v[12:13], off offset:576
	v_cmp_eq_u32_e32 vcc, 0, v17
	s_waitcnt vmcnt(4)
	v_and_b32_e32 v15, 0xffff0000, v18
	v_lshlrev_b32_e32 v14, 16, v18
	v_mul_f32_e32 v15, v15, v15
	v_fmac_f32_e32 v15, v14, v14
	v_lshlrev_b32_e32 v14, 16, v19
	v_fmac_f32_e32 v15, v14, v14
	v_and_b32_e32 v14, 0xffff0000, v19
	v_fmac_f32_e32 v15, v14, v14
	v_lshlrev_b32_e32 v14, 16, v20
	v_fmac_f32_e32 v15, v14, v14
	v_and_b32_e32 v14, 0xffff0000, v20
	v_fmac_f32_e32 v15, v14, v14
	v_lshlrev_b32_e32 v14, 16, v21
	v_fmac_f32_e32 v15, v14, v14
	v_and_b32_e32 v14, 0xffff0000, v21
	v_fmac_f32_e32 v15, v14, v14
	v_lshlrev_b32_e32 v14, 16, v8
	v_and_b32_e32 v8, 0xffff0000, v8
	v_mul_f32_e32 v8, v8, v8
	v_fmac_f32_e32 v8, v14, v14
	v_lshlrev_b32_e32 v14, 16, v9
	v_fmac_f32_e32 v8, v14, v14
	v_and_b32_e32 v9, 0xffff0000, v9
	v_fmac_f32_e32 v8, v9, v9
	v_lshlrev_b32_e32 v9, 16, v10
	v_fmac_f32_e32 v8, v9, v9
	v_and_b32_e32 v9, 0xffff0000, v10
	v_fmac_f32_e32 v8, v9, v9
	v_lshlrev_b32_e32 v9, 16, v11
	v_fmac_f32_e32 v8, v9, v9
	v_and_b32_e32 v9, 0xffff0000, v11
	v_fmac_f32_e32 v8, v9, v9
	v_lshlrev_b32_e32 v9, 16, v4
	v_and_b32_e32 v4, 0xffff0000, v4
	v_mul_f32_e32 v4, v4, v4
	v_fmac_f32_e32 v4, v9, v9
	v_lshlrev_b32_e32 v9, 16, v5
	v_fmac_f32_e32 v4, v9, v9
	v_and_b32_e32 v5, 0xffff0000, v5
	v_fmac_f32_e32 v4, v5, v5
	v_lshlrev_b32_e32 v5, 16, v6
	v_fmac_f32_e32 v4, v5, v5
	v_and_b32_e32 v5, 0xffff0000, v6
	v_fmac_f32_e32 v4, v5, v5
	v_lshlrev_b32_e32 v5, 16, v7
	v_fmac_f32_e32 v4, v5, v5
	v_and_b32_e32 v5, 0xffff0000, v7
	v_fmac_f32_e32 v4, v5, v5
	v_lshlrev_b32_e32 v5, 16, v0
	v_and_b32_e32 v0, 0xffff0000, v0
	v_mul_f32_e32 v0, v0, v0
	v_fmac_f32_e32 v0, v5, v5
	v_lshlrev_b32_e32 v5, 16, v1
	v_fmac_f32_e32 v0, v5, v5
	v_and_b32_e32 v1, 0xffff0000, v1
	v_fmac_f32_e32 v0, v1, v1
	v_lshlrev_b32_e32 v1, 16, v2
	v_fmac_f32_e32 v0, v1, v1
	v_and_b32_e32 v1, 0xffff0000, v2
	v_fmac_f32_e32 v0, v1, v1
	v_lshlrev_b32_e32 v1, 16, v3
	v_add_f32_e32 v8, v15, v8
	v_fmac_f32_e32 v0, v1, v1
	v_and_b32_e32 v1, 0xffff0000, v3
	v_add_f32_e32 v4, v8, v4
	v_fmac_f32_e32 v0, v1, v1
	v_add_f32_e32 v18, v4, v0
	s_waitcnt vmcnt(0)
; DEV float bflo(unsigned w) { return __uint_as_float(w << 16); }
; DEV float bfhi(unsigned w) { return __uint_as_float(w & 0xffff0000u); }
; DEV void row_scales(const u16* __restrict__ zrow0, int col0, int ncol, float* rs, int tid) {
;     ...
;   for (int i = 0; i < ncol / 2; i += 8) {
;     uint4 v = *(const uint4*)(s + i);
;     ss += bflo(v.x) * bflo(v.x) + bfhi(v.x) * bfhi(v.x) + bflo(v.y) * bflo(v.y) + bfhi(v.y) * bfhi(v.y) +
;           bflo(v.z) * bflo(v.z) + bfhi(v.z) * bfhi(v.z) + bflo(v.w) * bflo(v.w) + bfhi(v.w) * bfhi(v.w);
;   }
;   ss += shx(ss, 1, lane);
;   if (h == 0) rs[r] = rsqrtf(ss / (float)ncol + 1e-6f);
; }
; DEV void kvproj_item(const Params& p, int l, int tt, int tf, char* smem, int tid) {
;   const int t0 = tt * 192, f0 = tf * 128;
;   f32x4 acc[2][6];
;   zero_acc<2, 6>(acc);
;   float* rs = (float*)(smem + 122880);
;   __syncthreads();
;   row_scales(p.z + (long)t0 * NINP, C_CKV, 128, rs, tid);
;   gemm_mainloop<2, 6>(p.WukvT + ((long)l * 1024 + f0) * 128, 128, p.z + (long)t0 * NINP + C_CKV, NINP, 128, smem, tid, acc);
;   const int wid = tid >> 6, lane = tid & 63, fr = lane & 15, fq = lane >> 4, wn = wid & 3, wt = wid >> 2;
	v_lshlrev_b32_e32 v19, 16, v112
	v_and_b32_e32 v112, 0xffff0000, v112
	v_mul_f32_e32 v112, v112, v112
	v_fmac_f32_e32 v112, v19, v19
	v_lshlrev_b32_e32 v19, 16, v113
	v_fmac_f32_e32 v112, v19, v19
	v_and_b32_e32 v113, 0xffff0000, v113
	v_fmac_f32_e32 v112, v113, v113
	v_lshlrev_b32_e32 v113, 16, v114
	v_fmac_f32_e32 v112, v113, v113
	v_and_b32_e32 v113, 0xffff0000, v114
	v_fmac_f32_e32 v112, v113, v113
	v_lshlrev_b32_e32 v113, 16, v115
	v_fmac_f32_e32 v112, v113, v113
	v_and_b32_e32 v113, 0xffff0000, v115
	v_fmac_f32_e32 v112, v113, v113
	v_lshlrev_b32_e32 v113, 16, v108
	v_and_b32_e32 v108, 0xffff0000, v108
	v_mul_f32_e32 v108, v108, v108
	v_fmac_f32_e32 v108, v113, v113
	v_lshlrev_b32_e32 v113, 16, v109
	v_fmac_f32_e32 v108, v113, v113
	v_and_b32_e32 v109, 0xffff0000, v109
	v_fmac_f32_e32 v108, v109, v109
	v_lshlrev_b32_e32 v109, 16, v110
	v_fmac_f32_e32 v108, v109, v109
	v_and_b32_e32 v109, 0xffff0000, v110
	v_fmac_f32_e32 v108, v109, v109
	v_lshlrev_b32_e32 v109, 16, v111
	v_fmac_f32_e32 v108, v109, v109
	v_and_b32_e32 v109, 0xffff0000, v111
	v_fmac_f32_e32 v108, v109, v109
	v_lshlrev_b32_e32 v109, 16, v104
	v_and_b32_e32 v104, 0xffff0000, v104
	v_mul_f32_e32 v104, v104, v104
	v_fmac_f32_e32 v104, v109, v109
	v_lshlrev_b32_e32 v109, 16, v105
	v_fmac_f32_e32 v104, v109, v109
	v_and_b32_e32 v105, 0xffff0000, v105
	v_fmac_f32_e32 v104, v105, v105
	v_lshlrev_b32_e32 v105, 16, v106
	v_fmac_f32_e32 v104, v105, v105
	v_and_b32_e32 v105, 0xffff0000, v106
	v_fmac_f32_e32 v104, v105, v105
	v_lshlrev_b32_e32 v105, 16, v107
	v_fmac_f32_e32 v104, v105, v105
	v_and_b32_e32 v105, 0xffff0000, v107
	v_fmac_f32_e32 v104, v105, v105
	v_lshlrev_b32_e32 v105, 16, v100
	v_and_b32_e32 v100, 0xffff0000, v100
	v_mul_f32_e32 v100, v100, v100
	v_fmac_f32_e32 v100, v105, v105
	v_lshlrev_b32_e32 v105, 16, v101
	v_fmac_f32_e32 v100, v105, v105
	v_and_b32_e32 v101, 0xffff0000, v101
	v_fmac_f32_e32 v100, v101, v101
	v_lshlrev_b32_e32 v101, 16, v102
	v_fmac_f32_e32 v100, v101, v101
	v_and_b32_e32 v101, 0xffff0000, v102
	v_add_f32_e32 v112, v18, v112
	v_fmac_f32_e32 v100, v101, v101
	v_lshlrev_b32_e32 v101, 16, v103
	v_add_f32_e32 v108, v112, v108
	v_fmac_f32_e32 v100, v101, v101
	v_and_b32_e32 v101, 0xffff0000, v103
	v_add_f32_e32 v104, v108, v104
	v_fmac_f32_e32 v100, v101, v101
	v_lshlrev_b32_e32 v1, 2, v58
	v_add_f32_e32 v0, v104, v100
	v_bitop3_b32 v1, v1, 4, v252 bitop3:0x6c
	ds_bpermute_b32 v1, v1, v0
	s_and_b64 exec, exec, vcc
	s_cbranch_execz .LBB0_759
	s_waitcnt lgkmcnt(0)
	v_add_f32_e32 v0, v0, v1
	v_fmamk_f32 v0, v0, 0x3c000000, v196
	s_mov_b32 s16, 0x800000
	v_mul_f32_e32 v1, 0x4b800000, v0
	v_cmp_gt_f32_e32 vcc, s16, v0
	s_nop 1
	v_cndmask_b32_e32 v0, v0, v1, vcc
	v_rsq_f32_e32 v0, v0
	s_nop 0
	v_mul_f32_e32 v1, 0x45800000, v0
	v_cndmask_b32_e32 v0, v0, v1, vcc
	v_mov_b32_e32 v1, 0x1e000
	v_lshl_add_u32 v1, v16, 2, v1
	ds_write_b32 v1, v0
.LBB0_759:
	s_or_b64 exec, exec, s[8:9]
	s_mov_b32 s16, s98
	v_mov_b32_e32 v2, v133
	v_mov_b32_e32 v3, v134
	v_mov_b32_e32 v4, v135
	v_mov_b32_e32 v12, v136
	v_bfe_u32 v0, v58, 4, 2
	v_lshrrev_b32_e32 v1, 8, v58
	v_and_b32_e32 v49, 0x60, v3
	v_mul_i32_i24_e32 v1, 0x60, v1
	v_bitop3_b32 v0, v0, v4, 4 bitop3:0x36
	v_or_b32_e32 v3, v49, v2
	v_or_b32_e32 v48, v1, v2
	v_bitop3_b32 v1, v12, v4, 3 bitop3:0x6c
	v_lshlrev_b32_e32 v53, 4, v0
	v_mov_b32_e32 v0, 0
	v_lshlrev_b32_e32 v50, 4, v1
	v_lshlrev_b32_e32 v51, 7, v3
	v_lshlrev_b32_e32 v52, 7, v48
	s_mov_b64 s[6:7], 0
	s_mov_b64 s[8:9], -1
	v_mov_b32_e32 v1, v0
	v_mov_b32_e32 v2, v0
	v_mov_b32_e32 v3, v0
	v_mov_b32_e32 v4, v0
	v_mov_b32_e32 v5, v0
	v_mov_b32_e32 v6, v0
	v_mov_b32_e32 v7, v0
	v_mov_b32_e32 v8, v0
	v_mov_b32_e32 v9, v0
	v_mov_b32_e32 v10, v0
	v_mov_b32_e32 v11, v0
	v_mov_b32_e32 v12, v0
	v_mov_b32_e32 v13, v0
	v_mov_b32_e32 v14, v0
	v_mov_b32_e32 v15, v0
	v_mov_b32_e32 v16, v0
	v_mov_b32_e32 v17, v0
	v_mov_b32_e32 v18, v0
	v_mov_b32_e32 v19, v0
	v_mov_b32_e32 v20, v0
	v_mov_b32_e32 v21, v0
	v_mov_b32_e32 v22, v0
	v_mov_b32_e32 v23, v0
	v_mov_b32_e32 v24, v0
	v_mov_b32_e32 v25, v0
	v_mov_b32_e32 v26, v0
	v_mov_b32_e32 v27, v0
	v_mov_b32_e32 v28, v0
	v_mov_b32_e32 v29, v0
	v_mov_b32_e32 v30, v0
	v_mov_b32_e32 v31, v0
	v_mov_b32_e32 v32, v0
	v_mov_b32_e32 v33, v0
	v_mov_b32_e32 v34, v0
	v_mov_b32_e32 v35, v0
	v_mov_b32_e32 v36, v0
	v_mov_b32_e32 v37, v0
	v_mov_b32_e32 v38, v0
	v_mov_b32_e32 v39, v0
	v_mov_b32_e32 v40, v0
	v_mov_b32_e32 v41, v0
	v_mov_b32_e32 v42, v0
	v_mov_b32_e32 v43, v0
	v_mov_b32_e32 v44, v0
	v_mov_b32_e32 v45, v0
	v_mov_b32_e32 v46, v0
	v_mov_b32_e32 v47, v0
	s_branch .LBB0_761

; template <int WN, int WT>
; DEV void gemm_mainloop(const u16* __restrict__ Wt, long ldw, const u16* __restrict__ A, long lda, int K,
;                        char* smem, int tid, f32x4 (&acc)[WN][WT]) {
;     ...
;   __syncthreads();
;   stage_tile<NR>(Wt, ldw, 0, smem, tid);
;   stage_tile<TR>(A, lda, 0, smem + WB, tid);
;   if (nk > 1) {
;     stage_tile<NR>(Wt, ldw, 64, smem + STG, tid);
;     stage_tile<TR>(A, lda, 64, smem + STG + WB, tid);
;   }
; DEV void qproj_item(const Params& p, int l, int tt, int tf, char* smem, int tid) {
;   const int t0 = tt * 192, f0 = tf * 128;
;   f32x4 acc[2][6];
;   zero_acc<2, 6>(acc);
;   float* rs = (float*)(smem + 122880);
;   __syncthreads();
;   row_scales(p.z + (long)t0 * NINP, C_CQ, 256, rs, tid);
;   gemm_mainloop<2, 6>(p.WuqT + ((long)l * 768 + f0) * 256, 256, p.z + (long)t0 * NINP + C_CQ, NINP, 256, smem, tid, acc);
.LBB0_767:
	s_mul_i32 s6, s15, 43
	s_lshr_b32 s16, s6, 8
	s_mul_i32 s6, s16, 6
	s_sub_i32 s10, s15, s6
	s_cmp_eq_u32 s16, 0
	v_readlane_b32 s8, v255, 42
	s_cselect_b64 s[6:7], -1, 0
	v_readlane_b32 s9, v255, 43
	s_and_b64 s[6:7], s[8:9], s[6:7]
	s_and_b64 vcc, exec, s[6:7]
	s_cbranch_vccnz .LBB0_749
	v_readlane_b32 s6, v255, 10
	s_add_i32 s16, s16, s6
	s_mul_i32 s17, s16, 0xc0
	s_movk_i32 s8, 0x180
	s_mul_i32 s6, s16, 0x330000
	s_mul_hi_i32 s7, s17, 0x4400
	v_cmp_gt_i32_e32 vcc, s8, v58
	s_waitcnt vmcnt(0)
	s_barrier
	v_and_b32_e32 v132, 0xff, v197
	v_lshlrev_b32_e32 v132, 4, v132
	global_load_dwordx4 v[128:131], v132, s[82:83]
	s_lshl_b32 s8, s10, 7
	s_add_u32 s10, s88, s6
	s_addc_u32 s11, s89, s7
	s_ashr_i32 s9, s8, 31
	s_mul_i32 s18, s14, 0x300
	s_add_u32 s18, s8, s18
	s_addc_u32 s19, s9, 0
	v_readlane_b32 s40, v253, 7
	v_lshrrev_b32_e32 v18, 4, v58
	v_ashrrev_i32_e32 v2, 3, v58
	s_lshl_b64 s[18:19], s[18:19], 9
	v_readlane_b32 s46, v253, 13
	s_waitcnt lgkmcnt(0)
	v_xor_b32_e32 v0, v18, v58
	v_ashrrev_i32_e32 v3, 31, v2
	v_readlane_b32 s47, v253, 14
	s_add_u32 s18, s46, s18
	v_lshlrev_b32_e32 v0, 4, v0
	v_lshlrev_b64 v[4:5], 9, v[2:3]
	v_add_u32_e32 v3, 0x200, v58
	s_addc_u32 s19, s47, s19
	v_and_b32_e32 v156, 0x70, v0
	v_lshlrev_b32_e32 v59, 4, v58
	v_ashrrev_i32_e32 v8, 3, v3
	v_lshl_add_u64 v[0:1], s[18:19], 0, v[156:157]
	v_readfirstlane_b32 s18, v59
	v_ashrrev_i32_e32 v9, 31, v8
	v_lshlrev_b32_e32 v60, 4, v3
	v_lshl_add_u64 v[12:13], s[10:11], 0, v[156:157]
	v_lshl_add_u64 v[6:7], v[0:1], 0, v[4:5]
	s_mov_b32 m0, s18
	v_lshlrev_b64 v[10:11], 9, v[8:9]
	v_readfirstlane_b32 s18, v60
	v_mad_i64_i32 v[14:15], s[10:11], v2, s33, v[12:13]
	v_add_u32_e32 v3, 0x4000, v59
	s_barrier
	global_load_lds_dwordx4 v[6:7], off
	v_lshl_add_u64 v[0:1], v[0:1], 0, v[10:11]
	s_mov_b32 m0, s18
	v_readfirstlane_b32 s10, v3
	global_load_lds_dwordx4 v[0:1], off
	s_mov_b32 m0, s10
	v_mad_i64_i32 v[16:17], s[10:11], v8, s33, v[12:13]
	v_add_u32_e32 v3, 0x4000, v60
	global_load_lds_dwordx4 v[14:15], off
	v_readfirstlane_b32 s10, v3
	v_add_u32_e32 v3, 0x400, v58
	v_ashrrev_i32_e32 v9, 3, v3
	v_lshlrev_b32_e32 v61, 4, v3
	s_mov_b32 m0, s10
	v_mad_i64_i32 v[12:13], s[10:11], v9, s33, v[12:13]
	v_add_u32_e32 v3, 0x4000, v61
	global_load_lds_dwordx4 v[16:17], off
	v_readfirstlane_b32 s10, v3
	v_add_u32_e32 v3, 0xa000, v59
	s_mov_b32 m0, s10
	v_readfirstlane_b32 s10, v3
	v_add_u32_e32 v3, 0xa000, v60
	global_load_lds_dwordx4 v[12:13], off
	v_lshl_add_u64 v[6:7], v[6:7], 0, s[34:35]
	s_mov_b32 m0, s10
	v_readfirstlane_b32 s10, v3
	v_add_u32_e32 v3, 0xe000, v59
	global_load_lds_dwordx4 v[6:7], off
	v_lshl_add_u64 v[0:1], v[0:1], 0, s[34:35]
	s_mov_b32 m0, s10
	v_readfirstlane_b32 s10, v3
	v_add_u32_e32 v3, 0xe000, v60
	global_load_lds_dwordx4 v[0:1], off
	v_lshl_add_u64 v[0:1], v[14:15], 0, s[34:35]
	s_mov_b32 m0, s10
	v_readfirstlane_b32 s10, v3
	v_add_u32_e32 v3, 0xe000, v61
	global_load_lds_dwordx4 v[0:1], off
	v_lshl_add_u64 v[0:1], v[16:17], 0, s[34:35]
	s_mov_b32 m0, s10
	v_readfirstlane_b32 s10, v3
	global_load_lds_dwordx4 v[0:1], off
	v_lshl_add_u64 v[0:1], v[12:13], 0, s[34:35]
	s_mov_b32 m0, s10
	v_lshrrev_b32_e32 v63, 1, v58
	global_load_lds_dwordx4 v[0:1], off
	s_mov_b32 s98, s8
	s_mov_b32 s99, s9
	v_mov_b32_e32 v133, v2
	v_mov_b32_e32 v134, v4
	v_mov_b32_e32 v135, v5
	s_and_saveexec_b64 s[8:9], vcc
	s_cbranch_execz .LBB0_773
	v_ashrrev_i32_e32 v2, 1, v58
	v_mov_b64_e32 v[0:1], s[6:7]
	v_mad_i64_i32 v[0:1], s[18:19], v2, s33, v[0:1]
	v_and_b32_e32 v3, 1, v58
	v_lshlrev_b32_e32 v156, 8, v3
	v_readlane_b32 s18, v254, 37
	v_lshl_add_u64 v[0:1], v[0:1], 0, v[156:157]
	v_readlane_b32 s19, v254, 38
	v_mov_b32_e32 v4, 0
	s_mov_b32 s11, -8
	v_lshl_add_u64 v[0:1], s[18:19], 0, v[0:1]

; template <int WN, int WT>
; DEV void gemm_mainloop(const u16* __restrict__ Wt, long ldw, const u16* __restrict__ A, long lda, int K,
;                        char* smem, int tid, f32x4 (&acc)[WN][WT]) {
;   constexpr int NR = WN * 64, TR = WT * 32;
;   constexpr int WB = NR * 128, STG = (NR + TR) * 128;
;   constexpr int NLD = (NR + TR) / 64;
;   static_assert(3 * STG <= 147456, "LDS stages");
;   const int wid = tid >> 6, lane = tid & 63, fr = lane & 15, fq = lane >> 4, wn = wid & 3, wt = wid >> 2;
;   const int nk = K >> 6;
;   __syncthreads();
;   stage_tile<NR>(Wt, ldw, 0, smem, tid);
;   stage_tile<TR>(A, lda, 0, smem + WB, tid);
;   if (nk > 1) {
;     stage_tile<NR>(Wt, ldw, 64, smem + STG, tid);
;     stage_tile<TR>(A, lda, 64, smem + STG + WB, tid);
;   }
;   int cur = 0;
; DEV void qproj_item(const Params& p, int l, int tt, int tf, char* smem, int tid) {
;   const int t0 = tt * 192, f0 = tf * 128;
;   f32x4 acc[2][6];
;   zero_acc<2, 6>(acc);
;   float* rs = (float*)(smem + 122880);
;   __syncthreads();
;   row_scales(p.z + (long)t0 * NINP, C_CQ, 256, rs, tid);
;   gemm_mainloop<2, 6>(p.WuqT + ((long)l * 768 + f0) * 256, 256, p.z + (long)t0 * NINP + C_CQ, NINP, 256, smem, tid, acc);
.LBB0_773:
	s_or_b64 exec, exec, s[8:9]
	s_waitcnt vmcnt(0)
	v_add_u32_e32 v132, 0x1f000, v132
	ds_write_b128 v132, v[128:131]
	s_mov_b32 s8, s98
	s_mov_b32 s9, s99
	v_mov_b32_e32 v2, v133
	v_mov_b32_e32 v4, v134
	v_mov_b32_e32 v5, v135
	v_lshrrev_b32_e32 v0, 8, v58
	v_and_b32_e32 v1, 15, v58
	v_bfe_u32 v6, v58, 1, 3
	v_mul_i32_i24_e32 v0, 0x60, v0
	v_bfe_u32 v66, v58, 4, 2
	v_and_b32_e32 v64, 0x60, v63
	v_or_b32_e32 v62, v0, v1
	v_bitop3_b32 v0, v18, v6, 3 bitop3:0x6c
	v_or_b32_e32 v3, v64, v1
	v_lshlrev_b32_e32 v65, 4, v0
	v_bitop3_b32 v0, v66, v6, 4 bitop3:0x36
	v_lshlrev_b32_e32 v67, 7, v3
	v_lshlrev_b32_e32 v69, 4, v0
	v_mov_b64_e32 v[0:1], s[6:7]
	v_bitop3_b32 v3, v18, 7, v58 bitop3:0x48
	v_mad_i64_i32 v[6:7], s[6:7], v9, s33, v[0:1]
	v_lshlrev_b32_e32 v156, 4, v3
	v_readlane_b32 s10, v254, 39
	v_lshl_add_u64 v[6:7], v[6:7], 0, v[156:157]
	v_readlane_b32 s11, v254, 40
	v_lshlrev_b32_e32 v68, 7, v62
	s_mov_b32 s18, 0
	v_lshl_add_u64 v[48:49], s[10:11], 0, v[6:7]
	v_mad_i64_i32 v[6:7], s[6:7], v8, s33, v[0:1]
	v_mad_i64_i32 v[0:1], s[6:7], v2, s33, v[0:1]
	v_lshl_add_u64 v[6:7], v[6:7], 0, v[156:157]
	v_lshl_add_u64 v[0:1], v[0:1], 0, v[156:157]
	s_lshl_b64 s[6:7], s[8:9], 9
	v_lshl_add_u64 v[50:51], s[10:11], 0, v[6:7]
	v_lshl_add_u64 v[52:53], s[10:11], 0, v[0:1]
	v_lshl_add_u64 v[0:1], v[10:11], 0, s[6:7]
	v_readlane_b32 s10, v255, 34
	v_or_b32_e32 v0, v0, v156
	v_readlane_b32 s11, v255, 35
	s_mov_b32 s9, 0
	v_readlane_b32 s41, v253, 8
	v_lshl_add_u64 v[54:55], s[10:11], 0, v[0:1]
	v_lshl_add_u64 v[0:1], v[4:5], 0, s[6:7]
	v_or_b32_e32 v0, v0, v156
	v_lshl_add_u64 v[56:57], s[10:11], 0, v[0:1]
	v_mov_b32_e32 v0, 0
	s_mov_b64 s[6:7], 0
	v_mov_b32_e32 v1, v0
	v_mov_b32_e32 v2, v0
	v_mov_b32_e32 v3, v0
	v_mov_b32_e32 v4, v0
	v_mov_b32_e32 v5, v0
	v_mov_b32_e32 v6, v0
	v_mov_b32_e32 v7, v0
	v_mov_b32_e32 v8, v0
	v_mov_b32_e32 v9, v0
	v_mov_b32_e32 v10, v0
	v_mov_b32_e32 v11, v0
	v_mov_b32_e32 v12, v0
	v_mov_b32_e32 v13, v0
	v_mov_b32_e32 v14, v0
	v_mov_b32_e32 v15, v0
	v_mov_b32_e32 v16, v0
	v_mov_b32_e32 v17, v0
	v_mov_b32_e32 v18, v0
	v_mov_b32_e32 v19, v0
	v_mov_b32_e32 v20, v0
	v_mov_b32_e32 v21, v0
	v_mov_b32_e32 v22, v0
	v_mov_b32_e32 v23, v0
	v_mov_b32_e32 v24, v0
	v_mov_b32_e32 v25, v0
	v_mov_b32_e32 v26, v0
	v_mov_b32_e32 v27, v0
	v_mov_b32_e32 v28, v0
	v_mov_b32_e32 v29, v0
	v_mov_b32_e32 v30, v0
	v_mov_b32_e32 v31, v0
	v_mov_b32_e32 v32, v0
	v_mov_b32_e32 v33, v0
	v_mov_b32_e32 v34, v0
	v_mov_b32_e32 v35, v0
	v_mov_b32_e32 v36, v0
	v_mov_b32_e32 v37, v0
	v_mov_b32_e32 v38, v0
	v_mov_b32_e32 v39, v0
	v_mov_b32_e32 v40, v0
	v_mov_b32_e32 v41, v0
	v_mov_b32_e32 v42, v0
	v_mov_b32_e32 v43, v0
	v_mov_b32_e32 v44, v0
	v_mov_b32_e32 v45, v0
	v_mov_b32_e32 v46, v0
	v_mov_b32_e32 v47, v0
	v_readlane_b32 s42, v253, 9
	v_readlane_b32 s43, v253, 10
	v_readlane_b32 s44, v253, 11
	v_readlane_b32 s45, v253, 12
	v_readlane_b32 s48, v253, 15
	v_readlane_b32 s49, v253, 16
	v_readlane_b32 s50, v253, 17
	v_readlane_b32 s51, v253, 18
	v_readlane_b32 s52, v253, 19
	v_readlane_b32 s53, v253, 20
	v_readlane_b32 s54, v253, 21
	v_readlane_b32 s55, v253, 22
	s_branch .LBB0_775
